# GEMM-up: LDS tile image with address bits 9/10 swapped so each LDS-DMA fetches 8 rows x 128B full lines (staging offsets, read bases, ds_read immediates changed consistently); on top of v23
# speedup vs baseline: 1.0056x; 1.0047x over previous
; #define PG8_STAGE(bufoff, gbase, voff) do { _Pragma("unroll") for (int _i = 0; _i < 2; ++_i) \
;         __builtin_amdgcn_global_load_lds((const unsigned*)((const char*)(gbase) + (voff)[_i]), (PG8_LAS unsigned*)(lds + (bufoff) + ldsw + _i * 8192), 16, 0, 0); } while (0)
; #define PG8_WAIT_V(n) asm volatile("s_waitcnt vmcnt(" #n ")" ::: "memory")
; #define PG8_BAR __builtin_amdgcn_s_barrier()
; template <class Epi, class Sched, bool ALIGN_EPI = false, bool SP2 = false>
; __device__ __forceinline__ void gemm_phase(PG8_LAS unsigned char* lds, const Gemm g, const Sched& S, const Epi& E) {
;     ...
;     for (int i = 0; i < 2; ++i) { int R, C; stage_rc(tid * 16 + i * 8192, R, C); const int Rb = Epi::PERM ? ((R & ~31) + perm32(R & 31)) : R;
;         voffA[i] = (unsigned)(R * K + C) * 2u; voffB[i] = (unsigned)(Rb * K + C) * 2u; }
;     const size_t kstep = (size_t)(BK * 2);
;     const size_t hstep = (size_t)HALF * K * 2;
;     const size_t tstep = 2 * hstep;
;     const unsigned ldsw = (unsigned)wid * 1024u;
;     const int aoff = lds_byte(wr * 64 + fr, fq * 8), boff = lds_byte(wc * 32 + fr, fq * 8);
;     ...
;         PG8_STAGE(PG8_SB(0, 0), cB, voffB); PG8_STAGE(PG8_SB(0, 1), cB + hstep, voffB); PG8_STAGE(PG8_SA(0, 0), cA, voffA); PG8_STAGE(PG8_SA(0, 1), cA + hstep, voffA);
;         if (wr == 1) PG8_BAR;
;         PG8_WAIT_V(2); PG8_BAR;
;         PG8_STAGE(PG8_SB(1, 0), cB + kstep, voffB); PG8_STAGE(PG8_SA(1, 0), cA + kstep, voffA); PG8_STAGE(PG8_SB(1, 1), cB + hstep + kstep, voffB);
;         PG8_WAIT_V(6); PG8_BAR;
.LBB0_1234:
	v_ashrrev_i32_e32 v1, 31, v14
	v_lshrrev_b32_e32 v1, 26, v1
	v_add_u32_e32 v1, v14, v1
	v_ashrrev_i32_e32 v8, 6, v1
	v_bfe_i32 v1, v14, 27, 1
	v_lshlrev_b32_e32 v0, 4, v14
	v_lshrrev_b32_e32 v1, 22, v1
	v_add_u32_e32 v1, v0, v1
	v_and_b32_e32 v1, 0xfffffc00, v1
	v_sub_u32_e32 v1, v0, v1
	v_lshrrev_b32_e32 v2, 4, v1
	v_bitop3_b32 v1, v2, v1, 32 bitop3:0x6c
	s_mul_i32 s6, s62, 0x1a00000
	v_ashrrev_i32_e32 v3, 31, v1
	s_mul_hi_u32 s1, s62, 0x1a00000
	s_add_u32 s6, s4, s6
	v_lshrrev_b32_e32 v3, 26, v3
	s_addc_u32 s1, s5, s1
	v_add_u32_e32 v3, v1, v3
	s_add_u32 s20, s4, 0x6e00000
	v_lshlrev_b32_e32 v2, 3, v8
	v_ashrrev_i32_e32 v9, 6, v3
	v_and_b32_e32 v3, 0xc0, v3
	s_addc_u32 s61, s5, 0
	v_and_b32_e32 v2, -16, v2
	v_sub_u32_e32 v1, v1, v3
	s_add_u32 s80, s6, 0x1000000
	v_add_u32_e32 v2, v9, v2
	v_ashrrev_i16_sdwa v1, v220, sext(v1) dst_sel:DWORD dst_unused:UNUSED_PAD src0_sel:DWORD src1_sel:BYTE_0
	s_addc_u32 s81, s1, 0
	v_lshlrev_b32_e32 v4, 5, v8
	v_bfe_i32 v10, v1, 0, 16
	v_lshlrev_b32_e32 v1, 1, v2
	v_lshrrev_b32_e32 v3, 2, v2
	v_and_b32_e32 v5, 3, v9
	s_mov_b32 s1, 0x1fffe0
	v_and_b32_e32 v4, 32, v4
	v_and_b32_e32 v1, 24, v1
	v_and_b32_e32 v3, 4, v3
	v_and_or_b32 v5, v2, s1, v5
	v_or3_b32 v1, v5, v3, v1
	v_add_lshl_u32 v3, v4, v10, 1
	v_add_u32_e32 v0, 0x2000, v0
	v_lshl_add_u32 v162, v1, 11, v3
	v_and_b32_e32 v230, 63, v160
	v_lshrrev_b32_e32 v231, 6, v160
	v_bfe_u32 v232, v230, 2, 3
	v_lshrrev_b32_e32 v233, 5, v230
	v_and_b32_e32 v234, 3, v230
	v_and_b32_e32 v235, 1, v231
	v_lshlrev_b32_e32 v236, 1, v235
	v_xor_b32_e32 v234, v234, v236
	v_lshlrev_b32_e32 v234, 4, v234
	v_lshl_or_b32 v234, v233, 6, v234
	v_lshrrev_b32_e32 v236, 2, v231
	v_lshlrev_b32_e32 v236, 5, v236
	v_lshl_add_u32 v236, v235, 4, v236
	v_lshrrev_b32_e32 v235, 2, v232
	v_lshl_add_u32 v236, v235, 3, v236
	v_bfe_u32 v235, v231, 1, 1
	v_lshl_add_u32 v236, v235, 2, v236
	v_and_b32_e32 v235, 3, v232
	v_add_u32_e32 v236, v236, v235
	v_lshl_add_u32 v162, v236, 11, v234
	v_ashrrev_i32_e32 v1, 31, v0
	v_lshrrev_b32_e32 v1, 22, v1
	v_add_u32_e32 v1, v0, v1
	v_ashrrev_i32_e32 v11, 10, v1
	v_mul_i32_i24_e32 v1, 0x400, v11
	v_sub_u32_e32 v0, v0, v1
	v_lshrrev_b32_e32 v1, 4, v0
	v_bitop3_b32 v0, v1, v0, 32 bitop3:0x6c
	v_lshl_add_u32 v128, v2, 11, v3
	v_and_b32_e32 v230, 63, v160
	v_lshrrev_b32_e32 v231, 6, v160
	v_bfe_u32 v232, v230, 2, 3
	v_lshrrev_b32_e32 v233, 5, v230
	v_and_b32_e32 v234, 3, v230
	v_and_b32_e32 v235, 1, v231
	v_lshlrev_b32_e32 v236, 1, v235
	v_xor_b32_e32 v234, v234, v236
	v_lshlrev_b32_e32 v234, 4, v234
	v_lshl_or_b32 v234, v233, 6, v234
	v_lshl_add_u32 v236, v231, 3, v232
	v_lshl_add_u32 v128, v236, 11, v234
	v_ashrrev_i32_e32 v2, 31, v0
	v_lshrrev_b32_e32 v2, 26, v2
	v_lshlrev_b32_e32 v1, 3, v11
	v_add_u32_e32 v2, v0, v2
	v_and_b32_e32 v1, -16, v1
	v_ashrrev_i32_e32 v12, 6, v2
	v_add_u32_e32 v1, v12, v1
	v_and_b32_e32 v4, 3, v12
	s_add_i32 s0, s2, s0
	v_and_or_b32 v4, v1, s1, v4
	s_ashr_i32 s1, s0, 31
	s_lshr_b32 s1, s1, 26
	s_add_i32 s1, s0, s1
	s_ashr_i32 s2, s1, 6
	s_and_b32 s1, s1, 0xffc0
	s_sub_i32 s0, s0, s1
	s_bfe_i32 s1, s0, 0x80000
	s_bfe_u32 s1, s1, 0x2000d
	s_add_i32 s1, s0, s1
	s_lshl_b32 s16, s2, 2
	s_bfe_i32 s2, s1, 0x80000
	s_and_b32 s1, s1, 0xfc
	s_sub_i32 s0, s0, s1
	s_sext_i32_i16 s2, s2
	s_sext_i32_i8 s0, s0
	s_lshr_b32 s2, s2, 2
	s_add_i32 s72, s16, s0
	v_and_b32_e32 v2, 0xc0, v2
	s_ashr_i32 s7, s3, 6
	s_ashr_i32 s73, s72, 31
	s_bfe_i64 s[16:17], s[2:3], 0x100000
	s_ashr_i32 s6, s3, 8
	v_sub_u32_e32 v0, v0, v2
	s_lshl_b32 s82, s7, 10
	s_lshl_b64 s[0:1], s[72:73], 19
	s_lshl_b64 s[16:17], s[16:17], 19
	v_ashrrev_i16_sdwa v0, v220, sext(v0) dst_sel:DWORD dst_unused:UNUSED_PAD src0_sel:DWORD src1_sel:BYTE_0
	s_add_u32 s76, s80, s16
	v_lshlrev_b32_e32 v3, 5, v11
	v_bfe_i32 v13, v0, 0, 16
	v_lshlrev_b32_e32 v0, 1, v1
	v_lshrrev_b32_e32 v2, 2, v1
	s_addc_u32 s77, s81, s17
	s_add_i32 s73, s82, 0
	v_and_b32_e32 v3, 32, v3
	v_and_b32_e32 v0, 24, v0
	v_and_b32_e32 v2, 4, v2
	s_add_i32 m0, s73, 0x10000
	v_or3_b32 v0, v4, v2, v0
	v_add_lshl_u32 v2, v3, v13, 1
	global_load_lds_dwordx4 v162, s[76:77]
	s_add_i32 m0, s73, 0x12000
	v_lshl_add_u32 v132, v0, 11, v2
	v_and_b32_e32 v230, 63, v160
	v_lshrrev_b32_e32 v231, 6, v160
	v_bfe_u32 v232, v230, 2, 3
	v_lshrrev_b32_e32 v233, 5, v230
	v_and_b32_e32 v234, 3, v230
	v_and_b32_e32 v235, 1, v231
	v_lshlrev_b32_e32 v236, 1, v235
	v_xor_b32_e32 v234, v234, v236
	v_lshlrev_b32_e32 v234, 4, v234
	v_lshl_or_b32 v234, v233, 6, v234
	v_lshrrev_b32_e32 v236, 2, v231
	v_lshlrev_b32_e32 v236, 5, v236
	v_lshl_add_u32 v236, v235, 4, v236
	v_lshrrev_b32_e32 v235, 2, v232
	v_lshl_add_u32 v236, v235, 3, v236
	v_bfe_u32 v235, v231, 1, 1
	v_lshl_add_u32 v236, v235, 2, v236
	v_and_b32_e32 v235, 3, v232
	v_add_u32_e32 v236, v236, v235
	v_add_u32_e32 v236, 64, v236
	v_lshl_add_u32 v132, v236, 11, v234
	s_add_u32 s16, s76, 0x40000
	global_load_lds_dwordx4 v132, s[76:77]
	s_addc_u32 s17, s77, 0
	s_add_i32 m0, s73, 0x14000
	v_lshl_add_u32 v130, v1, 11, v2
	v_and_b32_e32 v230, 63, v160
	v_lshrrev_b32_e32 v231, 6, v160
	v_bfe_u32 v232, v230, 2, 3
	v_lshrrev_b32_e32 v233, 5, v230
	v_and_b32_e32 v234, 3, v230
	v_and_b32_e32 v235, 1, v231
	v_lshlrev_b32_e32 v236, 1, v235
	v_xor_b32_e32 v234, v234, v236
	v_lshlrev_b32_e32 v234, 4, v234
	v_lshl_or_b32 v234, v233, 6, v234
	v_lshl_add_u32 v236, v231, 3, v232
	v_add_u32_e32 v236, 64, v236
	v_lshl_add_u32 v130, v236, 11, v234
	global_load_lds_dwordx4 v162, s[16:17]
	s_add_i32 m0, s73, 0x16000
	s_add_u32 s74, s20, s0
	s_addc_u32 s75, s61, s1
	s_add_i32 s83, s73, 0x2000
	global_load_lds_dwordx4 v132, s[16:17]
	s_mov_b32 m0, s73
	s_add_u32 s0, s74, 0x40000
	global_load_lds_dwordx4 v128, s[74:75]
	s_mov_b32 m0, s83
	s_addc_u32 s1, s75, 0
	s_add_i32 s84, s73, 0x4000
	global_load_lds_dwordx4 v130, s[74:75]
	s_mov_b32 m0, s84
	s_add_i32 s85, s73, 0x6000
	global_load_lds_dwordx4 v128, s[0:1]
	s_mov_b32 m0, s85
	v_mov_b32_e32 v133, v163
	global_load_lds_dwordx4 v130, s[0:1]
	v_mov_b32_e32 v129, v163
	v_mov_b32_e32 v131, v163
	s_cmp_eq_u32 s6, 1
	v_lshl_add_u64 v[6:7], s[76:77], 0, v[162:163]
	v_lshl_add_u64 v[4:5], s[76:77], 0, v[132:133]
	v_lshl_add_u64 v[0:1], s[74:75], 0, v[128:129]
	s_cselect_b64 s[0:1], -1, 0
	s_cmp_lg_u32 s6, 1
	v_lshl_add_u64 v[2:3], s[74:75], 0, v[130:131]
	s_cbranch_scc1 .LBB0_1236
	s_barrier
; #define PG8_STAGE(bufoff, gbase, voff) do { _Pragma("unroll") for (int _i = 0; _i < 2; ++_i) \
;         __builtin_amdgcn_global_load_lds((const unsigned*)((const char*)(gbase) + (voff)[_i]), (PG8_LAS unsigned*)(lds + (bufoff) + ldsw + _i * 8192), 16, 0, 0); } while (0)
; #define PG8_WAIT_V(n) asm volatile("s_waitcnt vmcnt(" #n ")" ::: "memory")
; #define PG8_BAR __builtin_amdgcn_s_barrier()
; template <class Epi, class Sched, bool ALIGN_EPI = false, bool SP2 = false>
; __device__ __forceinline__ void gemm_phase(PG8_LAS unsigned char* lds, const Gemm g, const Sched& S, const Epi& E) {
;     ...
;     for (int i = 0; i < 2; ++i) { int R, C; stage_rc(tid * 16 + i * 8192, R, C); const int Rb = Epi::PERM ? ((R & ~31) + perm32(R & 31)) : R;
;         voffA[i] = (unsigned)(R * K + C) * 2u; voffB[i] = (unsigned)(Rb * K + C) * 2u; }
;     const size_t kstep = (size_t)(BK * 2);
;     const size_t hstep = (size_t)HALF * K * 2;
;     const size_t tstep = 2 * hstep;
;     const unsigned ldsw = (unsigned)wid * 1024u;
;     const int aoff = lds_byte(wr * 64 + fr, fq * 8), boff = lds_byte(wc * 32 + fr, fq * 8);
;     ...
;         PG8_STAGE(PG8_SB(0, 0), cB, voffB); PG8_STAGE(PG8_SB(0, 1), cB + hstep, voffB); PG8_STAGE(PG8_SA(0, 0), cA, voffA); PG8_STAGE(PG8_SA(0, 1), cA + hstep, voffA);
;         if (wr == 1) PG8_BAR;
;         PG8_WAIT_V(2); PG8_BAR;
;         PG8_STAGE(PG8_SB(1, 0), cB + kstep, voffB); PG8_STAGE(PG8_SA(1, 0), cA + kstep, voffA); PG8_STAGE(PG8_SB(1, 1), cB + hstep + kstep, voffB);
;         PG8_WAIT_V(6); PG8_BAR;
.LBB0_1236:
	v_lshrrev_b32_e32 v16, 1, v14
	v_and_b32_e32 v16, 24, v16
	s_add_u32 s4, s4, 0xae00000
	v_and_b32_e32 v15, 15, v14
	v_lshlrev_b32_e32 v17, 1, v16
	v_lshlrev_b32_e32 v14, 2, v14
	s_sext_i32_i8 s90, s2
	s_addc_u32 s5, s5, 0
	v_lshl_or_b32 v144, s6, 6, v15
	v_lshl_or_b32 v15, v15, 6, v17
	s_lshl_b32 s2, s6, 13
	v_and_b32_e32 v14, 32, v14
	v_bitop3_b32 v17, v15, s2, v14 bitop3:0xde
	s_lshl_b32 s2, s7, 5
	s_and_b32 s2, s2, 0x60
	s_add_i32 m0, s73, 0x18000
	v_lshl_add_u64 v[6:7], v[6:7], 0, s[22:23]
	s_lshl_b32 s6, s2, 7
	s_waitcnt vmcnt(2)
	s_barrier
	global_load_lds_dwordx4 v[6:7], off
	v_lshl_add_u64 v[4:5], v[4:5], 0, s[22:23]
	s_add_i32 m0, s73, 0x1a000
	s_add_i32 s86, s73, 0x8000
	s_add_i32 s87, s73, 0xa000
	v_bitop3_b32 v145, v15, s6, v14 bitop3:0xde
	v_and_b32_e32 v230, 0x200, v145
	v_add_u32_e32 v145, v145, v230
	global_load_lds_dwordx4 v[4:5], off
	v_lshl_add_u64 v[0:1], v[0:1], 0, s[22:23]
	s_mov_b32 m0, s86
	s_add_u32 s6, s76, 0x40080
	global_load_lds_dwordx4 v[0:1], off
	v_lshl_add_u64 v[0:1], v[2:3], 0, s[22:23]
	s_mov_b32 m0, s87
	s_addc_u32 s7, s77, 0
	global_load_lds_dwordx4 v[0:1], off
	s_add_i32 m0, s73, 0x1c000
	v_lshl_add_u64 v[0:1], s[6:7], 0, v[162:163]
	global_load_lds_dwordx4 v[0:1], off
	v_lshl_add_u64 v[0:1], s[6:7], 0, v[132:133]
	s_add_i32 m0, s73, 0x1e000
	s_cmpk_lt_u32 s3, 0x100
	global_load_lds_dwordx4 v[0:1], off
	v_lshlrev_b32_e32 v0, 14, v8
	v_and_b32_e32 v0, 0xffff8000, v0
	v_lshl_add_u32 v0, v9, 11, v0
	v_and_b32_e32 v1, 1, v8
	v_lshl_or_b32 v0, v1, 6, v0
	v_lshl_add_u32 v134, v10, 1, v0
	v_and_b32_e32 v230, 63, v160
	v_lshrrev_b32_e32 v231, 6, v160
	v_bfe_u32 v232, v230, 2, 3
	v_lshrrev_b32_e32 v233, 5, v230
	v_and_b32_e32 v234, 3, v230
	v_and_b32_e32 v235, 1, v231
	v_lshlrev_b32_e32 v236, 1, v235
	v_xor_b32_e32 v234, v234, v236
	v_lshlrev_b32_e32 v234, 4, v234
	v_lshl_or_b32 v234, v233, 6, v234
	v_lshl_add_u32 v236, v231, 3, v232
	v_lshl_add_u32 v134, v236, 11, v234
	v_lshlrev_b32_e32 v0, 14, v11
	v_and_b32_e32 v0, 0xffff8000, v0
	s_waitcnt vmcnt(6)
	v_lshl_add_u32 v0, v12, 11, v0
	v_and_b32_e32 v1, 1, v11
	v_lshl_or_b32 v0, v1, 6, v0
	s_cselect_b64 s[6:7], -1, 0
	s_ashr_i32 s88, s9, 31
	v_or_b32_e32 v146, s2, v16
	v_mov_b32_e32 v135, v163
	v_lshl_add_u32 v136, v13, 1, v0
	v_and_b32_e32 v230, 63, v160
	v_lshrrev_b32_e32 v231, 6, v160
	v_bfe_u32 v232, v230, 2, 3
	v_lshrrev_b32_e32 v233, 5, v230
	v_and_b32_e32 v234, 3, v230
	v_and_b32_e32 v235, 1, v231
	v_lshlrev_b32_e32 v236, 1, v235
	v_xor_b32_e32 v234, v234, v236
	v_lshlrev_b32_e32 v234, 4, v234
	v_lshl_or_b32 v234, v233, 6, v234
	v_lshl_add_u32 v236, v231, 3, v232
	v_add_u32_e32 v236, 64, v236
	v_lshl_add_u32 v136, v236, 11, v234
	v_mov_b32_e32 v137, v163
	s_mov_b32 s89, 0
	v_add_u32_e32 v147, 0, v17
	v_and_b32_e32 v230, 0x200, v147
	v_add_u32_e32 v147, v147, v230
	s_barrier
	s_branch .LBB0_1239

; #define PG8_STAGE(bufoff, gbase, voff) do { _Pragma("unroll") for (int _i = 0; _i < 2; ++_i) \
;         __builtin_amdgcn_global_load_lds((const unsigned*)((const char*)(gbase) + (voff)[_i]), (PG8_LAS unsigned*)(lds + (bufoff) + ldsw + _i * 8192), 16, 0, 0); } while (0)
; #define PG8_LDA(dst, b, h) do { _Pragma("unroll") for (int m = 0; m < 4; ++m) _Pragma("unroll") for (int k = 0; k < 2; ++k) dst[m][k] = *(const PG8_LAS bf16x8*)(lds + PG8_SA(b, h) + aoff + m * 2048 + k * 1024); } while (0)
; #define PG8_LDB(dst, b, h) do { _Pragma("unroll") for (int n = 0; n < 2; ++n) _Pragma("unroll") for (int k = 0; k < 2; ++k) dst[n][k] = *(const PG8_LAS bf16x8*)(lds + PG8_SB(b, h) + boff + n * 2048 + k * 1024); } while (0)
; #define PG8_MMA(ai, bj, At, Bt) do { __builtin_amdgcn_s_setprio(1); _Pragma("unroll") for (int m = 0; m < 4; ++m) _Pragma("unroll") for (int n = 0; n < 2; ++n) _Pragma("unroll") for (int k = 0; k < 2; ++k) \
;         acc[ai][bj][m][n] = __builtin_amdgcn_mfma_f32_16x16x32_bf16(Bt[n][k], At[m][k], acc[ai][bj][m][n], 0, 0, 0); __builtin_amdgcn_s_setprio(0); } while (0)
; #define PG8_WAIT_V(n) asm volatile("s_waitcnt vmcnt(" #n ")" ::: "memory")
; #define PG8_WAIT_L(n) asm volatile("s_waitcnt lgkmcnt(" #n ")" ::: "memory")
; #define PG8_BAR __builtin_amdgcn_s_barrier()
; #define PG8_SCHED __builtin_amdgcn_sched_barrier(0)
; template <class Epi, class Sched, bool ALIGN_EPI = false, bool SP2 = false>
; __device__ __forceinline__ void gemm_phase(PG8_LAS unsigned char* lds, const Gemm g, const Sched& S, const Epi& E) {
;     ...
;             PG8_LDB(B0, 0, 0); PG8_LDB(B1, 0, 1); PG8_SCHED; PG8_LDA(At, 0, 0); PG8_STAGE(PG8_SA(1, 1), a1 + hstep, voffA);
;             PG8_WAIT_V(8); PG8_WAIT_L(0); PG8_BAR; PG8_MMA(0, 0, At, B0); PG8_MMA(0, 1, At, B1); PG8_BAR; PG8_SCHED;
;             PG8_LDA(At, 0, 1); PG8_STAGE(PG8_SB(0, 0), b2, voffB); PG8_STAGE(PG8_SB(0, 1), b2 + hstep, voffB); PG8_STAGE(PG8_SA(0, 0), a2, voffA);
;             PG8_WAIT_V(8); PG8_WAIT_L(0); PG8_BAR; PG8_MMA(1, 0, At, B0); PG8_MMA(1, 1, At, B1); PG8_BAR; PG8_SCHED;
.LBB0_1246:
	s_add_u32 s19, s74, 0xfffc0080
	s_addc_u32 s34, s75, -1
	s_add_i32 s35, 0, 0x10000
	s_cmp_eq_u32 s92, 12
	s_cselect_b32 s79, s16, s34
	s_cselect_b32 s78, s17, s19
	v_add_u32_e32 v142, s35, v145
	s_cselect_b32 s77, s18, s91
	s_cselect_b32 s76, s65, s67
	s_add_i32 s19, 0, 0x14000
	ds_read_b128 v[138:141], v142
	ds_read_b128 v[148:151], v142 offset:512
	ds_read_b128 v[152:155], v142 offset:2048
	ds_read_b128 v[156:159], v142 offset:2560
	v_add_u32_e32 v142, s19, v145
	ds_read_b128 v[168:171], v142
	ds_read_b128 v[172:175], v142 offset:512
	ds_read_b128 v[178:181], v142 offset:2048
	ds_read_b128 v[182:185], v142 offset:2560
	v_lshl_add_u64 v[142:143], s[74:75], 0, v[134:135]
	s_add_i32 m0, s73, 0xc000
	ds_read_b128 v[186:189], v147
	ds_read_b128 v[190:193], v147 offset:512
	ds_read_b128 v[194:197], v147 offset:2048
	ds_read_b128 v[198:201], v147 offset:2560
	ds_read_b128 v[202:205], v147 offset:4096
	ds_read_b128 v[206:209], v147 offset:4608
	ds_read_b128 v[210:213], v147 offset:6144
	ds_read_b128 v[214:217], v147 offset:6656
	global_load_lds_dwordx4 v[142:143], off
	v_lshl_add_u64 v[142:143], s[74:75], 0, v[136:137]
	s_add_i32 m0, s73, 0xe000
	s_nop 0
	global_load_lds_dwordx4 v[142:143], off
	s_waitcnt vmcnt(8)
	s_waitcnt lgkmcnt(0)
	s_barrier
	s_setprio 1
	s_waitcnt lgkmcnt(0)
	v_mfma_f32_16x16x32_bf16 v[124:127], v[138:141], v[186:189], v[124:127]
	v_mfma_f32_16x16x32_bf16 v[120:123], v[152:155], v[186:189], v[120:123]
	v_mfma_f32_16x16x32_bf16 v[108:111], v[138:141], v[194:197], v[108:111]
	v_mfma_f32_16x16x32_bf16 v[104:107], v[152:155], v[194:197], v[104:107]
	v_mfma_f32_16x16x32_bf16 v[92:95], v[138:141], v[202:205], v[92:95]
	v_mfma_f32_16x16x32_bf16 v[88:91], v[152:155], v[202:205], v[88:91]
	v_mfma_f32_16x16x32_bf16 v[76:79], v[138:141], v[210:213], v[76:79]
	v_mfma_f32_16x16x32_bf16 v[72:75], v[152:155], v[210:213], v[72:75]
	v_mfma_f32_16x16x32_bf16 v[124:127], v[148:151], v[190:193], v[124:127]
	v_mfma_f32_16x16x32_bf16 v[120:123], v[156:159], v[190:193], v[120:123]
	v_mfma_f32_16x16x32_bf16 v[108:111], v[148:151], v[198:201], v[108:111]
	v_mfma_f32_16x16x32_bf16 v[104:107], v[156:159], v[198:201], v[104:107]
	v_mfma_f32_16x16x32_bf16 v[92:95], v[148:151], v[206:209], v[92:95]
	v_mfma_f32_16x16x32_bf16 v[88:91], v[156:159], v[206:209], v[88:91]
	v_mfma_f32_16x16x32_bf16 v[76:79], v[148:151], v[214:217], v[76:79]
	v_mfma_f32_16x16x32_bf16 v[72:75], v[156:159], v[214:217], v[72:75]
	s_setprio 0
	s_setprio 1
	v_mfma_f32_16x16x32_bf16 v[116:119], v[168:171], v[186:189], v[116:119]
	v_mfma_f32_16x16x32_bf16 v[112:115], v[178:181], v[186:189], v[112:115]
	v_mfma_f32_16x16x32_bf16 v[100:103], v[168:171], v[194:197], v[100:103]
	v_mfma_f32_16x16x32_bf16 v[96:99], v[178:181], v[194:197], v[96:99]
	v_mfma_f32_16x16x32_bf16 v[84:87], v[168:171], v[202:205], v[84:87]
	v_mfma_f32_16x16x32_bf16 v[80:83], v[178:181], v[202:205], v[80:83]
	v_mfma_f32_16x16x32_bf16 v[68:71], v[168:171], v[210:213], v[68:71]
	v_mfma_f32_16x16x32_bf16 v[64:67], v[178:181], v[210:213], v[64:67]
	v_mfma_f32_16x16x32_bf16 v[116:119], v[172:175], v[190:193], v[116:119]
	v_mfma_f32_16x16x32_bf16 v[112:115], v[182:185], v[190:193], v[112:115]
	v_mfma_f32_16x16x32_bf16 v[100:103], v[172:175], v[198:201], v[100:103]
	v_mfma_f32_16x16x32_bf16 v[96:99], v[182:185], v[198:201], v[96:99]
	v_mfma_f32_16x16x32_bf16 v[84:87], v[172:175], v[206:209], v[84:87]
	v_mfma_f32_16x16x32_bf16 v[80:83], v[182:185], v[206:209], v[80:83]
	v_mfma_f32_16x16x32_bf16 v[68:71], v[172:175], v[214:217], v[68:71]
	v_mfma_f32_16x16x32_bf16 v[64:67], v[182:185], v[214:217], v[64:67]
	s_setprio 0
	s_barrier
	s_add_i32 s34, s35, s82
	v_lshl_add_u64 v[142:143], s[76:77], 0, v[162:163]
	s_mov_b32 m0, s34
	ds_read_b128 v[186:189], v147 offset:16384
	ds_read_b128 v[190:193], v147 offset:16896
	ds_read_b128 v[194:197], v147 offset:18432
	ds_read_b128 v[198:201], v147 offset:18944
	ds_read_b128 v[202:205], v147 offset:20480
	ds_read_b128 v[206:209], v147 offset:20992
	ds_read_b128 v[210:213], v147 offset:22528
	ds_read_b128 v[214:217], v147 offset:23040
	global_load_lds_dwordx4 v[142:143], off
	s_add_i32 m0, s34, 0x2000
	s_add_u32 s94, s76, 0x40000
	v_lshl_add_u64 v[224:225], s[76:77], 0, v[132:133]
	s_addc_u32 s95, s77, 0
	s_add_i32 s19, s19, s82
	global_load_lds_dwordx4 v[224:225], off
	v_lshl_add_u64 v[226:227], s[94:95], 0, v[162:163]
	s_mov_b32 m0, s19
	v_lshl_add_u64 v[230:231], s[78:79], 0, v[130:131]
	global_load_lds_dwordx4 v[226:227], off
	v_lshl_add_u64 v[226:227], s[94:95], 0, v[132:133]
	s_add_i32 m0, s19, 0x2000
	s_nop 0
	global_load_lds_dwordx4 v[226:227], off
	v_lshl_add_u64 v[226:227], s[78:79], 0, v[128:129]
	s_mov_b32 m0, s73
	s_nop 0
	global_load_lds_dwordx4 v[226:227], off
	s_mov_b32 m0, s83
	s_nop 0
	global_load_lds_dwordx4 v[230:231], off
	s_waitcnt vmcnt(8)
	s_waitcnt lgkmcnt(0)
	s_barrier
; #define PG8_STAGE(bufoff, gbase, voff) do { _Pragma("unroll") for (int _i = 0; _i < 2; ++_i) \
;         __builtin_amdgcn_global_load_lds((const unsigned*)((const char*)(gbase) + (voff)[_i]), (PG8_LAS unsigned*)(lds + (bufoff) + ldsw + _i * 8192), 16, 0, 0); } while (0)
; #define PG8_LDA(dst, b, h) do { _Pragma("unroll") for (int m = 0; m < 4; ++m) _Pragma("unroll") for (int k = 0; k < 2; ++k) dst[m][k] = *(const PG8_LAS bf16x8*)(lds + PG8_SA(b, h) + aoff + m * 2048 + k * 1024); } while (0)
; #define PG8_LDB(dst, b, h) do { _Pragma("unroll") for (int n = 0; n < 2; ++n) _Pragma("unroll") for (int k = 0; k < 2; ++k) dst[n][k] = *(const PG8_LAS bf16x8*)(lds + PG8_SB(b, h) + boff + n * 2048 + k * 1024); } while (0)
; #define PG8_MMA(ai, bj, At, Bt) do { __builtin_amdgcn_s_setprio(1); _Pragma("unroll") for (int m = 0; m < 4; ++m) _Pragma("unroll") for (int n = 0; n < 2; ++n) _Pragma("unroll") for (int k = 0; k < 2; ++k) \
;         acc[ai][bj][m][n] = __builtin_amdgcn_mfma_f32_16x16x32_bf16(Bt[n][k], At[m][k], acc[ai][bj][m][n], 0, 0, 0); __builtin_amdgcn_s_setprio(0); } while (0)
; #define PG8_WAIT_V(n) asm volatile("s_waitcnt vmcnt(" #n ")" ::: "memory")
; #define PG8_WAIT_L(n) asm volatile("s_waitcnt lgkmcnt(" #n ")" ::: "memory")
; #define PG8_BAR __builtin_amdgcn_s_barrier()
; #define PG8_SCHED __builtin_amdgcn_sched_barrier(0)
; template <class Epi, class Sched, bool ALIGN_EPI = false, bool SP2 = false>
; __device__ __forceinline__ void gemm_phase(PG8_LAS unsigned char* lds, const Gemm g, const Sched& S, const Epi& E) {
;     ...
;             PG8_WAIT_V(8); PG8_WAIT_L(0); PG8_BAR; PG8_MMA(1, 0, At, B0); PG8_MMA(1, 1, At, B1); PG8_BAR; PG8_SCHED;
;             PG8_LDB(B0, 1, 0); PG8_LDB(B1, 1, 1); PG8_SCHED; PG8_LDA(At, 1, 0); PG8_STAGE(PG8_SA(0, 1), a2 + hstep, voffA);
;             PG8_WAIT_V(8); PG8_WAIT_L(0); PG8_BAR; PG8_MMA(0, 0, At, B0); PG8_MMA(0, 1, At, B1); PG8_BAR; PG8_SCHED;
	s_setprio 1
	s_waitcnt lgkmcnt(0)
	v_mfma_f32_16x16x32_bf16 v[60:63], v[138:141], v[186:189], v[60:63]
	v_mfma_f32_16x16x32_bf16 v[56:59], v[152:155], v[186:189], v[56:59]
	v_mfma_f32_16x16x32_bf16 v[44:47], v[138:141], v[194:197], v[44:47]
	v_mfma_f32_16x16x32_bf16 v[40:43], v[152:155], v[194:197], v[40:43]
	v_mfma_f32_16x16x32_bf16 v[28:31], v[138:141], v[202:205], v[28:31]
	v_mfma_f32_16x16x32_bf16 v[24:27], v[152:155], v[202:205], v[24:27]
	v_mfma_f32_16x16x32_bf16 v[12:15], v[138:141], v[210:213], v[12:15]
	v_mfma_f32_16x16x32_bf16 v[8:11], v[152:155], v[210:213], v[8:11]
	v_mfma_f32_16x16x32_bf16 v[60:63], v[148:151], v[190:193], v[60:63]
	v_mfma_f32_16x16x32_bf16 v[56:59], v[156:159], v[190:193], v[56:59]
	v_mfma_f32_16x16x32_bf16 v[44:47], v[148:151], v[198:201], v[44:47]
	v_mfma_f32_16x16x32_bf16 v[40:43], v[156:159], v[198:201], v[40:43]
	v_mfma_f32_16x16x32_bf16 v[28:31], v[148:151], v[206:209], v[28:31]
	v_mfma_f32_16x16x32_bf16 v[24:27], v[156:159], v[206:209], v[24:27]
	v_mfma_f32_16x16x32_bf16 v[12:15], v[148:151], v[214:217], v[12:15]
	v_mfma_f32_16x16x32_bf16 v[8:11], v[156:159], v[214:217], v[8:11]
	s_setprio 0
	s_setprio 1
	v_mfma_f32_16x16x32_bf16 v[52:55], v[168:171], v[186:189], v[52:55]
	v_mfma_f32_16x16x32_bf16 v[48:51], v[178:181], v[186:189], v[48:51]
	v_mfma_f32_16x16x32_bf16 v[36:39], v[168:171], v[194:197], v[36:39]
	v_mfma_f32_16x16x32_bf16 v[32:35], v[178:181], v[194:197], v[32:35]
	v_mfma_f32_16x16x32_bf16 v[20:23], v[168:171], v[202:205], v[20:23]
	v_mfma_f32_16x16x32_bf16 v[16:19], v[178:181], v[202:205], v[16:19]
	v_mfma_f32_16x16x32_bf16 v[4:7], v[168:171], v[210:213], v[4:7]
	v_mfma_f32_16x16x32_bf16 v[0:3], v[178:181], v[210:213], v[0:3]
	v_mfma_f32_16x16x32_bf16 v[52:55], v[172:175], v[190:193], v[52:55]
	v_mfma_f32_16x16x32_bf16 v[48:51], v[182:185], v[190:193], v[48:51]
	v_mfma_f32_16x16x32_bf16 v[36:39], v[172:175], v[198:201], v[36:39]
	v_mfma_f32_16x16x32_bf16 v[32:35], v[182:185], v[198:201], v[32:35]
	v_mfma_f32_16x16x32_bf16 v[20:23], v[172:175], v[206:209], v[20:23]
	v_mfma_f32_16x16x32_bf16 v[16:19], v[182:185], v[206:209], v[16:19]
	v_mfma_f32_16x16x32_bf16 v[4:7], v[172:175], v[214:217], v[4:7]
	v_mfma_f32_16x16x32_bf16 v[0:3], v[182:185], v[214:217], v[0:3]
	s_setprio 0
	s_barrier
	s_add_i32 s19, 0, 0x18000
	s_add_i32 s34, 0, 0x1c000
	v_add_u32_e32 v156, s19, v145
	v_add_u32_e32 v176, s34, v145
	ds_read_b128 v[138:141], v156
	ds_read_b128 v[148:151], v156 offset:512
	ds_read_b128 v[152:155], v156 offset:2048
	ds_read_b128 v[156:159], v156 offset:2560
	ds_read_b128 v[168:171], v176
	ds_read_b128 v[172:175], v176 offset:512
	ds_read_b128 v[178:181], v176 offset:2048
	ds_read_b128 v[182:185], v176 offset:2560
	s_add_u32 s78, s78, 0x40000
	s_addc_u32 s79, s79, 0
	s_mov_b32 m0, s84
	v_lshl_add_u64 v[232:233], s[78:79], 0, v[128:129]
	ds_read_b128 v[186:189], v147 offset:32768
	ds_read_b128 v[190:193], v147 offset:33280
	ds_read_b128 v[194:197], v147 offset:34816
	ds_read_b128 v[198:201], v147 offset:35328
	ds_read_b128 v[202:205], v147 offset:36864
	ds_read_b128 v[206:209], v147 offset:37376
	ds_read_b128 v[210:213], v147 offset:38912
	ds_read_b128 v[214:217], v147 offset:39424
	global_load_lds_dwordx4 v[232:233], off
	v_lshl_add_u64 v[232:233], s[78:79], 0, v[130:131]
	s_mov_b32 m0, s85
	s_nop 0
	global_load_lds_dwordx4 v[232:233], off
	s_waitcnt vmcnt(8)
	s_waitcnt lgkmcnt(0)
	s_barrier
	s_setprio 1
	s_waitcnt lgkmcnt(0)
	v_mfma_f32_16x16x32_bf16 v[124:127], v[138:141], v[186:189], v[124:127]
	v_mfma_f32_16x16x32_bf16 v[120:123], v[152:155], v[186:189], v[120:123]
	v_mfma_f32_16x16x32_bf16 v[108:111], v[138:141], v[194:197], v[108:111]
	v_mfma_f32_16x16x32_bf16 v[104:107], v[152:155], v[194:197], v[104:107]
	v_mfma_f32_16x16x32_bf16 v[92:95], v[138:141], v[202:205], v[92:95]
	v_mfma_f32_16x16x32_bf16 v[88:91], v[152:155], v[202:205], v[88:91]
	v_mfma_f32_16x16x32_bf16 v[76:79], v[138:141], v[210:213], v[76:79]
	v_mfma_f32_16x16x32_bf16 v[72:75], v[152:155], v[210:213], v[72:75]
	v_mfma_f32_16x16x32_bf16 v[124:127], v[148:151], v[190:193], v[124:127]
	v_mfma_f32_16x16x32_bf16 v[120:123], v[156:159], v[190:193], v[120:123]
	v_mfma_f32_16x16x32_bf16 v[108:111], v[148:151], v[198:201], v[108:111]
	v_mfma_f32_16x16x32_bf16 v[104:107], v[156:159], v[198:201], v[104:107]
	v_mfma_f32_16x16x32_bf16 v[92:95], v[148:151], v[206:209], v[92:95]
	v_mfma_f32_16x16x32_bf16 v[88:91], v[156:159], v[206:209], v[88:91]
	v_mfma_f32_16x16x32_bf16 v[76:79], v[148:151], v[214:217], v[76:79]
	v_mfma_f32_16x16x32_bf16 v[72:75], v[156:159], v[214:217], v[72:75]
	s_setprio 0
	s_setprio 1
	v_mfma_f32_16x16x32_bf16 v[116:119], v[168:171], v[186:189], v[116:119]
	v_mfma_f32_16x16x32_bf16 v[112:115], v[178:181], v[186:189], v[112:115]
	v_mfma_f32_16x16x32_bf16 v[100:103], v[168:171], v[194:197], v[100:103]
	v_mfma_f32_16x16x32_bf16 v[96:99], v[178:181], v[194:197], v[96:99]
	v_mfma_f32_16x16x32_bf16 v[84:87], v[168:171], v[202:205], v[84:87]
	v_mfma_f32_16x16x32_bf16 v[80:83], v[178:181], v[202:205], v[80:83]
	v_mfma_f32_16x16x32_bf16 v[68:71], v[168:171], v[210:213], v[68:71]
	v_mfma_f32_16x16x32_bf16 v[64:67], v[178:181], v[210:213], v[64:67]
	v_mfma_f32_16x16x32_bf16 v[116:119], v[172:175], v[190:193], v[116:119]
	v_mfma_f32_16x16x32_bf16 v[112:115], v[182:185], v[190:193], v[112:115]
	v_mfma_f32_16x16x32_bf16 v[100:103], v[172:175], v[198:201], v[100:103]
	v_mfma_f32_16x16x32_bf16 v[96:99], v[182:185], v[198:201], v[96:99]
	v_mfma_f32_16x16x32_bf16 v[84:87], v[172:175], v[206:209], v[84:87]
	v_mfma_f32_16x16x32_bf16 v[80:83], v[182:185], v[206:209], v[80:83]
	v_mfma_f32_16x16x32_bf16 v[68:71], v[172:175], v[214:217], v[68:71]
	v_mfma_f32_16x16x32_bf16 v[64:67], v[182:185], v[214:217], v[64:67]
	s_setprio 0
	s_barrier
; #define PG8_STAGE(bufoff, gbase, voff) do { _Pragma("unroll") for (int _i = 0; _i < 2; ++_i) \
;         __builtin_amdgcn_global_load_lds((const unsigned*)((const char*)(gbase) + (voff)[_i]), (PG8_LAS unsigned*)(lds + (bufoff) + ldsw + _i * 8192), 16, 0, 0); } while (0)
; #define PG8_LDA(dst, b, h) do { _Pragma("unroll") for (int m = 0; m < 4; ++m) _Pragma("unroll") for (int k = 0; k < 2; ++k) dst[m][k] = *(const PG8_LAS bf16x8*)(lds + PG8_SA(b, h) + aoff + m * 2048 + k * 1024); } while (0)
; #define PG8_MMA(ai, bj, At, Bt) do { __builtin_amdgcn_s_setprio(1); _Pragma("unroll") for (int m = 0; m < 4; ++m) _Pragma("unroll") for (int n = 0; n < 2; ++n) _Pragma("unroll") for (int k = 0; k < 2; ++k) \
;         acc[ai][bj][m][n] = __builtin_amdgcn_mfma_f32_16x16x32_bf16(Bt[n][k], At[m][k], acc[ai][bj][m][n], 0, 0, 0); __builtin_amdgcn_s_setprio(0); } while (0)
; #define PG8_WAIT_V(n) asm volatile("s_waitcnt vmcnt(" #n ")" ::: "memory")
; #define PG8_WAIT_L(n) asm volatile("s_waitcnt lgkmcnt(" #n ")" ::: "memory")
; #define PG8_BAR __builtin_amdgcn_s_barrier()
; #define PG8_SCHED __builtin_amdgcn_sched_barrier(0)
; template <class Epi, class Sched, bool ALIGN_EPI = false, bool SP2 = false>
; __device__ __forceinline__ void gemm_phase(PG8_LAS unsigned char* lds, const Gemm g, const Sched& S, const Epi& E) {
;     ...
;         for (int t = 0; t < nt; t += 2) {
;             const bool last = (t == nt - 2);
;             const char* a1 = cA + (size_t)(t + 1) * kstep;
;             const char* a2 = last ? nA : cA + (size_t)(t + 2) * kstep; const char* b2 = last ? nB : cB + (size_t)(t + 2) * kstep;
;     ...
;             PG8_WAIT_V(8); PG8_WAIT_L(0); PG8_BAR; PG8_MMA(0, 0, At, B0); PG8_MMA(0, 1, At, B1); PG8_BAR; PG8_SCHED;
;             PG8_LDA(At, 1, 1); PG8_STAGE(PG8_SB(1, 0), b3, voffB); PG8_STAGE(PG8_SB(1, 1), b3 + hstep, voffB); PG8_STAGE(PG8_SA(1, 0), a3, voffA);
;             PG8_WAIT_V(8); PG8_WAIT_L(0); PG8_BAR; PG8_MMA(1, 0, At, B0); PG8_MMA(1, 1, At, B1); PG8_BAR; PG8_SCHED;
	s_add_i32 s19, s19, s82
	v_lshl_add_u64 v[142:143], v[142:143], 0, s[22:23]
	s_mov_b32 m0, s19
	ds_read_b128 v[186:189], v147 offset:49152
	ds_read_b128 v[190:193], v147 offset:49664
	ds_read_b128 v[194:197], v147 offset:51200
	ds_read_b128 v[198:201], v147 offset:51712
	ds_read_b128 v[202:205], v147 offset:53248
	ds_read_b128 v[206:209], v147 offset:53760
	ds_read_b128 v[210:213], v147 offset:55296
	ds_read_b128 v[214:217], v147 offset:55808
	global_load_lds_dwordx4 v[142:143], off
	s_add_i32 m0, s19, 0x2000
	s_add_u32 s76, s76, 0x40080
	v_lshl_add_u64 v[142:143], v[224:225], 0, s[22:23]
	s_addc_u32 s77, s77, 0
	s_add_i32 s19, s34, s82
	global_load_lds_dwordx4 v[142:143], off
	v_lshl_add_u64 v[142:143], s[76:77], 0, v[162:163]
	s_mov_b32 m0, s19
	s_nop 0
	global_load_lds_dwordx4 v[142:143], off
	v_lshl_add_u64 v[142:143], s[76:77], 0, v[132:133]
	s_add_i32 m0, s19, 0x2000
	s_nop 0
	global_load_lds_dwordx4 v[142:143], off
	v_lshl_add_u64 v[142:143], v[226:227], 0, s[22:23]
	s_mov_b32 m0, s86
	s_nop 0
	global_load_lds_dwordx4 v[142:143], off
	v_lshl_add_u64 v[142:143], v[230:231], 0, s[22:23]
	s_mov_b32 m0, s87
	s_nop 0
	global_load_lds_dwordx4 v[142:143], off
	s_waitcnt vmcnt(8)
	s_waitcnt lgkmcnt(0)
	s_barrier
	s_setprio 1
	s_waitcnt lgkmcnt(0)
	v_mfma_f32_16x16x32_bf16 v[60:63], v[138:141], v[186:189], v[60:63]
	v_mfma_f32_16x16x32_bf16 v[56:59], v[152:155], v[186:189], v[56:59]
	v_mfma_f32_16x16x32_bf16 v[44:47], v[138:141], v[194:197], v[44:47]
	v_mfma_f32_16x16x32_bf16 v[40:43], v[152:155], v[194:197], v[40:43]
	v_mfma_f32_16x16x32_bf16 v[28:31], v[138:141], v[202:205], v[28:31]
	v_mfma_f32_16x16x32_bf16 v[24:27], v[152:155], v[202:205], v[24:27]
	v_mfma_f32_16x16x32_bf16 v[12:15], v[138:141], v[210:213], v[12:15]
	v_mfma_f32_16x16x32_bf16 v[8:11], v[152:155], v[210:213], v[8:11]
	v_mfma_f32_16x16x32_bf16 v[60:63], v[148:151], v[190:193], v[60:63]
	v_mfma_f32_16x16x32_bf16 v[56:59], v[156:159], v[190:193], v[56:59]
	v_mfma_f32_16x16x32_bf16 v[44:47], v[148:151], v[198:201], v[44:47]
	v_mfma_f32_16x16x32_bf16 v[40:43], v[156:159], v[198:201], v[40:43]
	v_mfma_f32_16x16x32_bf16 v[28:31], v[148:151], v[206:209], v[28:31]
	v_mfma_f32_16x16x32_bf16 v[24:27], v[156:159], v[206:209], v[24:27]
	v_mfma_f32_16x16x32_bf16 v[12:15], v[148:151], v[214:217], v[12:15]
	v_mfma_f32_16x16x32_bf16 v[8:11], v[156:159], v[214:217], v[8:11]
	s_setprio 0
	s_setprio 1
	v_mfma_f32_16x16x32_bf16 v[52:55], v[168:171], v[186:189], v[52:55]
	v_mfma_f32_16x16x32_bf16 v[48:51], v[178:181], v[186:189], v[48:51]
	v_mfma_f32_16x16x32_bf16 v[36:39], v[168:171], v[194:197], v[36:39]
	v_mfma_f32_16x16x32_bf16 v[32:35], v[178:181], v[194:197], v[32:35]
	v_mfma_f32_16x16x32_bf16 v[20:23], v[168:171], v[202:205], v[20:23]
	v_mfma_f32_16x16x32_bf16 v[16:19], v[178:181], v[202:205], v[16:19]
	v_mfma_f32_16x16x32_bf16 v[4:7], v[168:171], v[210:213], v[4:7]
	v_mfma_f32_16x16x32_bf16 v[0:3], v[178:181], v[210:213], v[0:3]
	v_mfma_f32_16x16x32_bf16 v[52:55], v[172:175], v[190:193], v[52:55]
	v_mfma_f32_16x16x32_bf16 v[48:51], v[182:185], v[190:193], v[48:51]
	v_mfma_f32_16x16x32_bf16 v[36:39], v[172:175], v[198:201], v[36:39]
	v_mfma_f32_16x16x32_bf16 v[32:35], v[182:185], v[198:201], v[32:35]
	v_mfma_f32_16x16x32_bf16 v[20:23], v[172:175], v[206:209], v[20:23]
	v_mfma_f32_16x16x32_bf16 v[16:19], v[182:185], v[206:209], v[16:19]
	v_mfma_f32_16x16x32_bf16 v[4:7], v[172:175], v[214:217], v[4:7]
	v_mfma_f32_16x16x32_bf16 v[0:3], v[182:185], v[214:217], v[0:3]
	s_setprio 0
	s_barrier
	s_add_i32 s92, s92, 2
	s_add_u32 s74, s74, 0x100
	s_addc_u32 s75, s75, 0
	s_add_u32 s67, s67, 0x100
	s_addc_u32 s91, s91, 0
	s_cmp_gt_u32 s92, 13
	s_cbranch_scc0 .LBB0_1246
	s_and_b64 vcc, exec, s[6:7]
	s_cbranch_vccz .LBB0_1249
	s_barrier
